# scan loops: next-token kk prefetch through rotating operand bank; P transition update uses v_mfma_f32_32x32x1_2b_f32 (2 rank-1 blocks per instruction)
# speedup vs baseline: 1.0291x; 1.0053x over previous
.LBB0_362:
	s_add_i32 s12, s21, -7
	s_and_b64 s[22:23], s[2:3], exec
	s_cselect_b32 s15, s21, s12
	s_add_i32 s12, s15, -1
	s_max_i32 s12, s12, s14
	s_min_i32 s12, s12, s17
	s_mulk_i32 s12, 0x1800
	v_lshl_add_u64 v[130:131], v[158:159], 0, s[12:13]
	s_max_i32 s12, s15, s14
	s_min_i32 s12, s12, s17
	s_mulk_i32 s12, 0x1800
	v_lshl_add_u64 v[132:133], v[158:159], 0, s[12:13]
	s_add_i32 s12, s15, 1
	s_max_i32 s12, s12, s14
	s_min_i32 s12, s12, s17
	s_mulk_i32 s12, 0x1800
	v_lshl_add_u64 v[134:135], v[158:159], 0, s[12:13]
	s_add_i32 s12, s15, 2
	s_max_i32 s12, s12, s14
	s_min_i32 s12, s12, s17
	s_mulk_i32 s12, 0x1800
	v_lshl_add_u64 v[136:137], v[158:159], 0, s[12:13]
	s_add_i32 s12, s15, 3
	s_max_i32 s12, s12, s14
	s_min_i32 s12, s12, s17
	s_mulk_i32 s12, 0x1800
	v_lshl_add_u64 v[138:139], v[158:159], 0, s[12:13]
	s_add_i32 s12, s15, 4
	s_max_i32 s12, s12, s14
	s_min_i32 s12, s12, s17
	s_mulk_i32 s12, 0x1800
	v_lshl_add_u64 v[140:141], v[158:159], 0, s[12:13]
	s_add_i32 s12, s15, 5
	s_max_i32 s12, s12, s14
	s_min_i32 s12, s12, s17
	s_mulk_i32 s12, 0x1800
	v_lshl_add_u64 v[142:143], v[158:159], 0, s[12:13]
	s_add_i32 s12, s15, 6
	s_max_i32 s12, s12, s14
	s_min_i32 s12, s12, s17
	s_mulk_i32 s12, 0x1800
	v_lshl_add_u64 v[144:145], v[158:159], 0, s[12:13]
	s_add_i32 s12, s15, 7
	global_load_ushort v236, v[130:131], off
	global_load_ushort v233, v[132:133], off
	global_load_ushort v235, v[134:135], off
	global_load_ushort v232, v[136:137], off
	global_load_ushort v230, v[138:139], off
	global_load_ushort v229, v[140:141], off
	global_load_ushort v228, v[142:143], off
	global_load_ushort v227, v[144:145], off
	s_max_i32 s12, s12, s14
	s_min_i32 s12, s12, s17
	s_mulk_i32 s12, 0x1800
	s_add_i32 s15, s15, 8
	v_lshl_add_u64 v[130:131], v[158:159], 0, s[12:13]
	s_max_i32 s12, s15, s14
	s_min_i32 s12, s12, s17
	s_mulk_i32 s12, 0x1800
	v_lshl_add_u64 v[132:133], v[158:159], 0, s[12:13]
	global_load_ushort v234, v[130:131], off
	global_load_ushort v231, v[132:133], off
	s_waitcnt lgkmcnt(0)
	v_and_b32_e32 v132, 15, v1
	v_lshrrev_b32_e32 v133, 4, v1
	v_lshl_add_u32 v132, v132, 2, v133
	v_lshl_add_u32 v130, v132, 2, s18
	v_lshl_add_u32 v131, v1, 2, s18
	ds_read_b32 v138, v130 offset:768
	ds_read_b32 v139, v130 offset:2304
	ds_read_b32 v140, v130 offset:3840
	ds_read_b32 v141, v130 offset:5376
	ds_read_b32 v142, v130 offset:6912
	ds_read_b32 v143, v130 offset:8448
	ds_read_b32 v144, v130 offset:9984
	ds_read_b32 v145, v130 offset:11520
	v_and_b32_e32 v132, 31, v1
	v_lshrrev_b32_e32 v133, 5, v1
	v_lshlrev_b32_e32 v160, 4, v133
	v_lshlrev_b32_e32 v134, 8, v133
	v_lshl_add_u32 v237, v132, 2, v134
	v_add_u32_e32 v237, 0x100, v237
	v_lshlrev_b32_e32 v135, 2, v132
	v_sub_u32_e32 v255, v135, v134
	v_add_u32_e32 v255, 0x200, v255
	s_mov_b32 s98, 0
	s_mov_b32 s99, -1
	s_waitcnt lgkmcnt(0)
	ds_write_b32 v131, v138 offset:768
	ds_write_b32 v131, v139 offset:2304
	ds_write_b32 v131, v140 offset:3840
	ds_write_b32 v131, v141 offset:5376
	ds_write_b32 v131, v142 offset:6912
	ds_write_b32 v131, v143 offset:8448
	ds_write_b32 v131, v144 offset:9984
	ds_write_b32 v131, v145 offset:11520
	v_add_u32_e32 v253, s18, v160
	s_waitcnt lgkmcnt(0)
	ds_read_b128 v[130:133], v253 offset:768
	ds_read_b128 v[134:137], v253 offset:800
	ds_read_b128 v[138:141], v253 offset:832
	ds_read_b128 v[142:145], v253 offset:864
	ds_read_b128 v[146:149], v253 offset:896
	ds_read_b128 v[150:153], v253 offset:928
	ds_read_b128 v[154:157], v253 offset:960
	ds_read_b128 v[162:165], v253 offset:992
.LBB0_363:
	s_add_i32 s12, s18, s16
	v_add_u32_e32 v253, s12, v160
	v_add_u32_e32 v238, s12, v237
	v_add_u32_e32 v239, s12, v255
	v_xor_b32_e32 v240, 32, v1
	s_add_i32 s100, s12, 0x500
	v_lshl_add_u32 v240, v240, 2, s100
	ds_read_b32 v252, v240
	ds_read_b32 v248, v238
	ds_read_b32 v249, v238 offset:128
	ds_read_b32 v250, v239
	ds_read_b32 v251, v239 offset:128
	s_add_i32 s100, s12, 0x100
	v_lshl_add_u32 v241, v1, 2, s100
	ds_read_b32 v246, v241
	s_waitcnt lgkmcnt(13)
	v_pk_mul_f32 v[166:167], v[2:3], v[130:131]
	v_pk_mul_f32 v[168:169], v[34:35], v[130:131]
	v_pk_mul_f32 v[238:239], v[66:67], v[130:131]
	v_pk_mul_f32 v[240:241], v[98:99], v[130:131]
	v_pk_fma_f32 v[166:167], v[4:5], v[132:133], v[166:167]
	v_pk_fma_f32 v[168:169], v[36:37], v[132:133], v[168:169]
	v_pk_fma_f32 v[238:239], v[68:69], v[132:133], v[238:239]
	v_pk_fma_f32 v[240:241], v[100:101], v[132:133], v[240:241]
	ds_read_b128 v[130:133], v253 offset:0
	s_waitcnt lgkmcnt(13)
	v_pk_fma_f32 v[166:167], v[6:7], v[134:135], v[166:167]
	v_pk_fma_f32 v[168:169], v[38:39], v[134:135], v[168:169]
	v_pk_fma_f32 v[238:239], v[70:71], v[134:135], v[238:239]
	v_pk_fma_f32 v[240:241], v[102:103], v[134:135], v[240:241]
	v_pk_fma_f32 v[166:167], v[8:9], v[136:137], v[166:167]
	v_pk_fma_f32 v[168:169], v[40:41], v[136:137], v[168:169]
	v_pk_fma_f32 v[238:239], v[72:73], v[136:137], v[238:239]
	v_pk_fma_f32 v[240:241], v[104:105], v[136:137], v[240:241]
	ds_read_b128 v[134:137], v253 offset:32
	s_waitcnt lgkmcnt(13)
	v_pk_fma_f32 v[166:167], v[10:11], v[138:139], v[166:167]
	v_pk_fma_f32 v[168:169], v[42:43], v[138:139], v[168:169]
	v_pk_fma_f32 v[238:239], v[74:75], v[138:139], v[238:239]
	v_pk_fma_f32 v[240:241], v[106:107], v[138:139], v[240:241]
	v_pk_fma_f32 v[166:167], v[12:13], v[140:141], v[166:167]
	v_pk_fma_f32 v[168:169], v[44:45], v[140:141], v[168:169]
	v_pk_fma_f32 v[238:239], v[76:77], v[140:141], v[238:239]
	v_pk_fma_f32 v[240:241], v[108:109], v[140:141], v[240:241]
	ds_read_b128 v[138:141], v253 offset:64
	s_waitcnt lgkmcnt(13)
	v_pk_fma_f32 v[166:167], v[14:15], v[142:143], v[166:167]
	v_pk_fma_f32 v[168:169], v[46:47], v[142:143], v[168:169]
	v_pk_fma_f32 v[238:239], v[78:79], v[142:143], v[238:239]
	v_pk_fma_f32 v[240:241], v[110:111], v[142:143], v[240:241]
	v_pk_fma_f32 v[166:167], v[16:17], v[144:145], v[166:167]
	v_pk_fma_f32 v[168:169], v[48:49], v[144:145], v[168:169]
	v_pk_fma_f32 v[238:239], v[80:81], v[144:145], v[238:239]
	v_pk_fma_f32 v[240:241], v[112:113], v[144:145], v[240:241]
	ds_read_b128 v[142:145], v253 offset:96
	s_waitcnt lgkmcnt(13)
	v_pk_fma_f32 v[166:167], v[18:19], v[146:147], v[166:167]
	v_pk_fma_f32 v[168:169], v[50:51], v[146:147], v[168:169]
	v_pk_fma_f32 v[238:239], v[82:83], v[146:147], v[238:239]
	v_pk_fma_f32 v[240:241], v[114:115], v[146:147], v[240:241]
	v_pk_fma_f32 v[166:167], v[20:21], v[148:149], v[166:167]
	v_pk_fma_f32 v[168:169], v[52:53], v[148:149], v[168:169]
	v_pk_fma_f32 v[238:239], v[84:85], v[148:149], v[238:239]
	v_pk_fma_f32 v[240:241], v[116:117], v[148:149], v[240:241]
	ds_read_b128 v[146:149], v253 offset:128
	s_waitcnt lgkmcnt(13)
	v_pk_fma_f32 v[166:167], v[22:23], v[150:151], v[166:167]
	v_pk_fma_f32 v[168:169], v[54:55], v[150:151], v[168:169]
	v_pk_fma_f32 v[238:239], v[86:87], v[150:151], v[238:239]
	v_pk_fma_f32 v[240:241], v[118:119], v[150:151], v[240:241]
	v_pk_fma_f32 v[166:167], v[24:25], v[152:153], v[166:167]
	v_pk_fma_f32 v[168:169], v[56:57], v[152:153], v[168:169]
	v_pk_fma_f32 v[238:239], v[88:89], v[152:153], v[238:239]
	v_pk_fma_f32 v[240:241], v[120:121], v[152:153], v[240:241]
	ds_read_b128 v[150:153], v253 offset:160
	s_waitcnt lgkmcnt(13)
	v_pk_fma_f32 v[166:167], v[26:27], v[154:155], v[166:167]
	v_pk_fma_f32 v[168:169], v[58:59], v[154:155], v[168:169]
	v_pk_fma_f32 v[238:239], v[90:91], v[154:155], v[238:239]
	v_pk_fma_f32 v[240:241], v[122:123], v[154:155], v[240:241]
	v_pk_fma_f32 v[166:167], v[28:29], v[156:157], v[166:167]
	v_pk_fma_f32 v[168:169], v[60:61], v[156:157], v[168:169]
	v_pk_fma_f32 v[238:239], v[92:93], v[156:157], v[238:239]
	v_pk_fma_f32 v[240:241], v[124:125], v[156:157], v[240:241]
	ds_read_b128 v[154:157], v253 offset:192
	s_waitcnt lgkmcnt(13)
	v_pk_fma_f32 v[166:167], v[30:31], v[162:163], v[166:167]
	v_pk_fma_f32 v[168:169], v[62:63], v[162:163], v[168:169]
	v_pk_fma_f32 v[238:239], v[94:95], v[162:163], v[238:239]
	v_pk_fma_f32 v[240:241], v[126:127], v[162:163], v[240:241]
	v_pk_fma_f32 v[166:167], v[32:33], v[164:165], v[166:167]
	v_pk_fma_f32 v[168:169], v[64:65], v[164:165], v[168:169]
	v_pk_fma_f32 v[238:239], v[96:97], v[164:165], v[238:239]
	v_pk_fma_f32 v[240:241], v[128:129], v[164:165], v[240:241]
	ds_read_b128 v[162:165], v253 offset:224
	v_add_f32_e32 v244, v238, v239
	v_add_f32_e32 v245, v240, v241
	v_add_f32_e32 v242, v166, v167
	v_add_f32_e32 v243, v168, v169
	s_nop 0
	s_nop 0
	v_permlane32_swap_b32_e32 v244, v245
	v_permlane32_swap_b32_e32 v242, v243
	s_nop 0
	v_add_f32_e32 v247, v244, v245
	v_sub_f32_e64 v166, -v242, v243
	s_waitcnt lgkmcnt(13)
	v_cndmask_b32_e64 v168, -v247, v252, s[98:99]
	v_mov_b32_e32 v167, v166
	v_cndmask_b32_e64 v169, v252, -v247, s[98:99]
	s_nop 0
	v_permlane32_swap_b32_e32 v166, v167
	s_waitcnt lgkmcnt(4)
	v_pk_mul_f32 v[66:67], v[66:67], v[130:131]
	v_pk_mul_f32 v[68:69], v[68:69], v[132:133]
	v_pk_mul_f32 v[70:71], v[70:71], v[134:135]
	v_pk_mul_f32 v[72:73], v[72:73], v[136:137]
	v_pk_mul_f32 v[74:75], v[74:75], v[138:139]
	v_pk_mul_f32 v[76:77], v[76:77], v[140:141]
	v_pk_mul_f32 v[78:79], v[78:79], v[142:143]
	v_pk_mul_f32 v[80:81], v[80:81], v[144:145]
	s_waitcnt lgkmcnt(4)
	v_pk_mul_f32 v[98:99], v[98:99], v[130:131]
	v_pk_mul_f32 v[100:101], v[100:101], v[132:133]
	v_pk_mul_f32 v[102:103], v[102:103], v[134:135]
	v_pk_mul_f32 v[104:105], v[104:105], v[136:137]
	v_pk_mul_f32 v[106:107], v[106:107], v[138:139]
	v_pk_mul_f32 v[108:109], v[108:109], v[140:141]
	v_pk_mul_f32 v[110:111], v[110:111], v[142:143]
	v_pk_mul_f32 v[112:113], v[112:113], v[144:145]
	s_waitcnt lgkmcnt(9)
	v_mfma_f32_32x32x2_f32 v[66:81], v248, v168, v[66:81]
	s_waitcnt lgkmcnt(4)
	v_pk_mul_f32 v[2:3], v[2:3], v[130:131]
	v_pk_mul_f32 v[4:5], v[4:5], v[132:133]
	v_pk_mul_f32 v[6:7], v[6:7], v[134:135]
	v_pk_mul_f32 v[8:9], v[8:9], v[136:137]
	v_pk_mul_f32 v[10:11], v[10:11], v[138:139]
	v_pk_mul_f32 v[12:13], v[12:13], v[140:141]
	v_pk_mul_f32 v[14:15], v[14:15], v[142:143]
	v_pk_mul_f32 v[16:17], v[16:17], v[144:145]
	v_mfma_f32_32x32x2_f32 v[98:113], v250, v169, v[98:113]
	s_waitcnt lgkmcnt(0)
	v_pk_mul_f32 v[18:19], v[18:19], v[146:147]
	v_pk_mul_f32 v[20:21], v[20:21], v[148:149]
	v_pk_mul_f32 v[22:23], v[22:23], v[150:151]
	v_pk_mul_f32 v[24:25], v[24:25], v[152:153]
	v_pk_mul_f32 v[26:27], v[26:27], v[154:155]
	v_pk_mul_f32 v[28:29], v[28:29], v[156:157]
	v_pk_mul_f32 v[30:31], v[30:31], v[162:163]
	v_pk_mul_f32 v[32:33], v[32:33], v[164:165]
	s_waitcnt lgkmcnt(4)
	v_pk_mul_f32 v[34:35], v[34:35], v[130:131]
	v_pk_mul_f32 v[36:37], v[36:37], v[132:133]
	v_pk_mul_f32 v[38:39], v[38:39], v[134:135]
	v_pk_mul_f32 v[40:41], v[40:41], v[136:137]
	v_pk_mul_f32 v[42:43], v[42:43], v[138:139]
	v_pk_mul_f32 v[44:45], v[44:45], v[140:141]
	v_pk_mul_f32 v[46:47], v[46:47], v[142:143]
	v_pk_mul_f32 v[48:49], v[48:49], v[144:145]
	s_waitcnt lgkmcnt(8)
	v_mfma_f32_32x32x1_2b_f32 v[2:33], v246, v166, v[2:33]
	s_waitcnt lgkmcnt(0)
	v_pk_mul_f32 v[50:51], v[50:51], v[146:147]
	v_pk_mul_f32 v[52:53], v[52:53], v[148:149]
	v_pk_mul_f32 v[54:55], v[54:55], v[150:151]
	v_pk_mul_f32 v[56:57], v[56:57], v[152:153]
	v_pk_mul_f32 v[58:59], v[58:59], v[154:155]
	v_pk_mul_f32 v[60:61], v[60:61], v[156:157]
	v_pk_mul_f32 v[62:63], v[62:63], v[162:163]
	v_pk_mul_f32 v[64:65], v[64:65], v[164:165]
	s_waitcnt lgkmcnt(0)
	v_pk_mul_f32 v[82:83], v[82:83], v[146:147]
	v_pk_mul_f32 v[84:85], v[84:85], v[148:149]
	v_pk_mul_f32 v[86:87], v[86:87], v[150:151]
	v_pk_mul_f32 v[88:89], v[88:89], v[152:153]
	v_pk_mul_f32 v[90:91], v[90:91], v[154:155]
	v_pk_mul_f32 v[92:93], v[92:93], v[156:157]
	v_pk_mul_f32 v[94:95], v[94:95], v[162:163]
	v_pk_mul_f32 v[96:97], v[96:97], v[164:165]
	v_mfma_f32_32x32x1_2b_f32 v[34:65], v246, v167, v[34:65]
	s_waitcnt lgkmcnt(0)
	v_pk_mul_f32 v[114:115], v[114:115], v[146:147]
	v_pk_mul_f32 v[116:117], v[116:117], v[148:149]
	v_pk_mul_f32 v[118:119], v[118:119], v[150:151]
	v_pk_mul_f32 v[120:121], v[120:121], v[152:153]
	v_pk_mul_f32 v[122:123], v[122:123], v[154:155]
	v_pk_mul_f32 v[124:125], v[124:125], v[156:157]
	v_pk_mul_f32 v[126:127], v[126:127], v[162:163]
	v_pk_mul_f32 v[128:129], v[128:129], v[164:165]
	v_mfma_f32_32x32x2_f32 v[82:97], v249, v168, v[82:97]
	ds_read_b128 v[130:133], v253 offset:2304
	ds_read_b128 v[134:137], v253 offset:2336
	ds_read_b128 v[138:141], v253 offset:2368
	ds_read_b128 v[142:145], v253 offset:2400
	ds_read_b128 v[146:149], v253 offset:2432
	ds_read_b128 v[150:153], v253 offset:2464
	ds_read_b128 v[154:157], v253 offset:2496
	ds_read_b128 v[162:165], v253 offset:2528
	s_addk_i32 s16, 0x600
	s_cmpk_eq_i32 s16, 0x3000
	v_mfma_f32_32x32x2_f32 v[114:129], v251, v169, v[114:129]
	s_cbranch_scc0 .LBB0_363
	s_waitcnt lgkmcnt(0)
	s_cmp_eq_u32 s20, 26
	s_cbranch_scc0 .LBB0_335
	s_ashr_i32 s1, s0, 31
	s_lshl_b64 s[0:1], s[0:1], 15
	s_add_u32 s0, s88, s0
	s_addc_u32 s1, s89, s1
	v_and_b32_e32 v130, 31, v1
	v_lshrrev_b32_e32 v131, 5, v1
	v_lshlrev_b32_e32 v130, 8, v130
	v_lshl_add_u32 v130, v131, 4, v130
	v_mov_b32_e32 v131, 0
	v_lshl_add_u64 v[130:131], s[0:1], 0, v[130:131]
	s_mov_b64 s[0:1], 0x6180000
	v_lshl_add_u64 v[130:131], v[130:131], 0, s[0:1]
	s_mov_b64 s[0:1], 0x2000
	v_lshl_add_u64 v[132:133], v[130:131], 0, s[0:1]
	v_lshl_add_u64 v[136:137], v[132:133], 0, s[0:1]
	v_lshl_add_u64 v[138:139], v[136:137], 0, s[0:1]
	s_nop 8
	s_nop 8
	global_store_dwordx4 v[130:131], v[2:5], off
	global_store_dwordx4 v[130:131], v[6:9], off offset:32
	global_store_dwordx4 v[130:131], v[10:13], off offset:64
	global_store_dwordx4 v[130:131], v[14:17], off offset:96
	global_store_dwordx4 v[130:131], v[18:21], off offset:128
	global_store_dwordx4 v[130:131], v[22:25], off offset:160
	global_store_dwordx4 v[130:131], v[26:29], off offset:192
	global_store_dwordx4 v[130:131], v[30:33], off offset:224
	global_store_dwordx4 v[132:133], v[34:37], off
	global_store_dwordx4 v[132:133], v[38:41], off offset:32
	global_store_dwordx4 v[132:133], v[42:45], off offset:64
	global_store_dwordx4 v[132:133], v[46:49], off offset:96
	global_store_dwordx4 v[132:133], v[50:53], off offset:128
	global_store_dwordx4 v[132:133], v[54:57], off offset:160
	global_store_dwordx4 v[132:133], v[58:61], off offset:192
	global_store_dwordx4 v[132:133], v[62:65], off offset:224
	global_store_dwordx4 v[136:137], v[66:69], off
	global_store_dwordx4 v[136:137], v[70:73], off offset:32
	global_store_dwordx4 v[136:137], v[74:77], off offset:64
	global_store_dwordx4 v[136:137], v[78:81], off offset:96
	global_store_dwordx4 v[136:137], v[82:85], off offset:128
	global_store_dwordx4 v[136:137], v[86:89], off offset:160
	global_store_dwordx4 v[136:137], v[90:93], off offset:192
	global_store_dwordx4 v[136:137], v[94:97], off offset:224
	global_store_dwordx4 v[138:139], v[98:101], off
	global_store_dwordx4 v[138:139], v[102:105], off offset:32
	global_store_dwordx4 v[138:139], v[106:109], off offset:64
	global_store_dwordx4 v[138:139], v[110:113], off offset:96
	global_store_dwordx4 v[138:139], v[114:117], off offset:128
	global_store_dwordx4 v[138:139], v[118:121], off offset:160
	global_store_dwordx4 v[138:139], v[122:125], off offset:192
	global_store_dwordx4 v[138:139], v[126:129], off offset:224

.LBB0_728:
	s_or_b64 exec, exec, s[8:9]
	s_setprio 0
	s_waitcnt lgkmcnt(0)
	v_and_b32_e32 v84, 15, v1
	v_lshrrev_b32_e32 v85, 4, v1
	v_lshl_add_u32 v84, v84, 2, v85
	v_lshl_add_u32 v82, v84, 2, s30
	v_lshl_add_u32 v83, v1, 2, s30
	ds_read_b32 v66, v82 offset:768
	ds_read_b32 v67, v82 offset:1024
	ds_read_b32 v68, v82 offset:2304
	ds_read_b32 v69, v82 offset:2560
	ds_read_b32 v70, v82 offset:3840
	ds_read_b32 v71, v82 offset:4096
	ds_read_b32 v72, v82 offset:5376
	ds_read_b32 v73, v82 offset:5632
	ds_read_b32 v74, v82 offset:6912
	ds_read_b32 v75, v82 offset:7168
	ds_read_b32 v76, v82 offset:8448
	ds_read_b32 v77, v82 offset:8704
	ds_read_b32 v78, v82 offset:9984
	ds_read_b32 v79, v82 offset:10240
	ds_read_b32 v80, v82 offset:11520
	ds_read_b32 v81, v82 offset:11776
	v_and_b32_e32 v84, 31, v1
	v_lshrrev_b32_e32 v85, 5, v1
	v_lshlrev_b32_e32 v240, 4, v85
	v_lshlrev_b32_e32 v86, 8, v85
	v_lshl_add_u32 v241, v84, 2, v86
	v_add_u32_e32 v241, 0x100, v241
	v_lshlrev_b32_e32 v87, 2, v84
	v_sub_u32_e32 v242, v87, v86
	v_add_u32_e32 v242, 0x200, v242
	v_xor_b32_e32 v87, 32, v1
	v_lshlrev_b32_e32 v87, 2, v87
	v_add_u32_e32 v243, 0x500, v87
	s_mov_b32 s98, 0
	s_mov_b32 s99, -1
	s_waitcnt lgkmcnt(0)
	ds_write_b32 v83, v66 offset:768
	ds_write_b32 v83, v67 offset:1024
	ds_write_b32 v83, v68 offset:2304
	ds_write_b32 v83, v69 offset:2560
	ds_write_b32 v83, v70 offset:3840
	ds_write_b32 v83, v71 offset:4096
	ds_write_b32 v83, v72 offset:5376
	ds_write_b32 v83, v73 offset:5632
	ds_write_b32 v83, v74 offset:6912
	ds_write_b32 v83, v75 offset:7168
	ds_write_b32 v83, v76 offset:8448
	ds_write_b32 v83, v77 offset:8704
	ds_write_b32 v83, v78 offset:9984
	ds_write_b32 v83, v79 offset:10240
	ds_write_b32 v83, v80 offset:11520
	ds_write_b32 v83, v81 offset:11776
	v_add_u32_e32 v229, s30, v240
	s_waitcnt lgkmcnt(0)
	ds_read_b128 v[66:69], v229 offset:768
	ds_read_b128 v[70:73], v229 offset:800
	ds_read_b128 v[74:77], v229 offset:832
	ds_read_b128 v[78:81], v229 offset:864
	ds_read_b128 v[82:85], v229 offset:896
	ds_read_b128 v[86:89], v229 offset:928
	ds_read_b128 v[90:93], v229 offset:960
	ds_read_b128 v[94:97], v229 offset:992
	s_mov_b32 s8, 8
	s_mov_b32 s9, s30
	s_mov_b32 s18, s12
.LBB0_729:
	v_add_u32_e32 v229, s9, v240
	v_add_u32_e32 v232, s9, v243
	v_add_u32_e32 v230, s9, v241
	v_add_u32_e32 v231, s9, v242
	v_mov_b32_e32 v233, s18
	ds_read_b32 v224, v232
	ds_read_b32 v225, v233
	ds_read_b32 v150, v230
	ds_read_b32 v152, v230 offset:128
	ds_read_b32 v153, v231
	ds_read_b32 v154, v231 offset:128
	s_waitcnt lgkmcnt(13)
	v_pk_mul_f32 v[130:131], v[2:3], v[66:67]
	v_pk_mul_f32 v[132:133], v[4:5], v[68:69]
	v_pk_mul_f32 v[134:135], v[34:35], v[66:67]
	v_pk_mul_f32 v[136:137], v[36:37], v[68:69]
	ds_read_b128 v[66:69], v229 offset:0
	s_waitcnt lgkmcnt(13)
	v_pk_fma_f32 v[130:131], v[6:7], v[70:71], v[130:131]
	v_pk_fma_f32 v[132:133], v[8:9], v[72:73], v[132:133]
	v_pk_fma_f32 v[134:135], v[38:39], v[70:71], v[134:135]
	v_pk_fma_f32 v[136:137], v[40:41], v[72:73], v[136:137]
	ds_read_b128 v[70:73], v229 offset:32
	s_waitcnt lgkmcnt(13)
	v_pk_fma_f32 v[130:131], v[10:11], v[74:75], v[130:131]
	v_pk_fma_f32 v[132:133], v[12:13], v[76:77], v[132:133]
	v_pk_fma_f32 v[134:135], v[42:43], v[74:75], v[134:135]
	v_pk_fma_f32 v[136:137], v[44:45], v[76:77], v[136:137]
	ds_read_b128 v[74:77], v229 offset:64
	s_waitcnt lgkmcnt(13)
	v_pk_fma_f32 v[130:131], v[14:15], v[78:79], v[130:131]
	v_pk_fma_f32 v[132:133], v[16:17], v[80:81], v[132:133]
	v_pk_fma_f32 v[134:135], v[46:47], v[78:79], v[134:135]
	v_pk_fma_f32 v[136:137], v[48:49], v[80:81], v[136:137]
	ds_read_b128 v[78:81], v229 offset:96
	s_waitcnt lgkmcnt(13)
	v_pk_fma_f32 v[130:131], v[18:19], v[82:83], v[130:131]
	v_pk_fma_f32 v[132:133], v[20:21], v[84:85], v[132:133]
	v_pk_fma_f32 v[134:135], v[50:51], v[82:83], v[134:135]
	v_pk_fma_f32 v[136:137], v[52:53], v[84:85], v[136:137]
	ds_read_b128 v[82:85], v229 offset:128
	s_waitcnt lgkmcnt(13)
	v_pk_fma_f32 v[130:131], v[22:23], v[86:87], v[130:131]
	v_pk_fma_f32 v[132:133], v[24:25], v[88:89], v[132:133]
	v_pk_fma_f32 v[134:135], v[54:55], v[86:87], v[134:135]
	v_pk_fma_f32 v[136:137], v[56:57], v[88:89], v[136:137]
	ds_read_b128 v[86:89], v229 offset:160
	s_waitcnt lgkmcnt(13)
	v_pk_fma_f32 v[130:131], v[26:27], v[90:91], v[130:131]
	v_pk_fma_f32 v[132:133], v[28:29], v[92:93], v[132:133]
	v_pk_fma_f32 v[134:135], v[58:59], v[90:91], v[134:135]
	v_pk_fma_f32 v[136:137], v[60:61], v[92:93], v[136:137]
	ds_read_b128 v[90:93], v229 offset:192
	s_waitcnt lgkmcnt(13)
	v_pk_fma_f32 v[130:131], v[30:31], v[94:95], v[130:131]
	v_pk_fma_f32 v[132:133], v[32:33], v[96:97], v[132:133]
	v_pk_fma_f32 v[134:135], v[62:63], v[94:95], v[134:135]
	v_pk_fma_f32 v[136:137], v[64:65], v[96:97], v[136:137]
	ds_read_b128 v[94:97], v229 offset:224
	v_pk_add_f32 v[130:131], v[130:131], v[132:133]
	v_pk_add_f32 v[134:135], v[134:135], v[136:137]
	v_add_f32_e32 v226, v130, v131
	v_add_f32_e32 v227, v134, v135
	ds_read_b128 v[98:101], v229 offset:1024
	ds_read_b128 v[102:105], v229 offset:1056
	ds_read_b128 v[114:117], v229 offset:1152
	ds_read_b128 v[118:121], v229 offset:1184
	v_permlane32_swap_b32_e32 v226, v227
	ds_read_b128 v[106:109], v229 offset:1088
	ds_read_b128 v[110:113], v229 offset:1120
	ds_read_b128 v[122:125], v229 offset:1216
	ds_read_b128 v[126:129], v229 offset:1248
	v_add_f32_e32 v228, v226, v227
	s_waitcnt lgkmcnt(14)
	v_cndmask_b32_e64 v155, -v228, v224, s[98:99]
	v_cndmask_b32_e64 v223, v224, -v228, s[98:99]
	s_waitcnt lgkmcnt(12)
	v_pk_mul_f32 v[2:3], v[2:3], v[66:67]
	v_pk_mul_f32 v[4:5], v[4:5], v[68:69]
	v_pk_mul_f32 v[6:7], v[6:7], v[70:71]
	v_pk_mul_f32 v[8:9], v[8:9], v[72:73]
	v_pk_mul_f32 v[10:11], v[10:11], v[74:75]
	v_pk_mul_f32 v[12:13], v[12:13], v[76:77]
	v_pk_mul_f32 v[14:15], v[14:15], v[78:79]
	v_pk_mul_f32 v[16:17], v[16:17], v[80:81]
	s_waitcnt lgkmcnt(12)
	v_pk_mul_f32 v[34:35], v[34:35], v[66:67]
	v_pk_mul_f32 v[36:37], v[36:37], v[68:69]
	v_pk_mul_f32 v[38:39], v[38:39], v[70:71]
	v_pk_mul_f32 v[40:41], v[40:41], v[72:73]
	v_pk_mul_f32 v[42:43], v[42:43], v[74:75]
	v_pk_mul_f32 v[44:45], v[44:45], v[76:77]
	v_pk_mul_f32 v[46:47], v[46:47], v[78:79]
	v_pk_mul_f32 v[48:49], v[48:49], v[80:81]
	s_waitcnt lgkmcnt(14)
	v_mfma_f32_32x32x2_f32 v[2:17], v150, v155, v[2:17]
	s_waitcnt lgkmcnt(8)
	v_pk_mul_f32 v[18:19], v[18:19], v[82:83]
	v_pk_mul_f32 v[20:21], v[20:21], v[84:85]
	v_pk_mul_f32 v[22:23], v[22:23], v[86:87]
	v_pk_mul_f32 v[24:25], v[24:25], v[88:89]
	v_pk_mul_f32 v[26:27], v[26:27], v[90:91]
	v_pk_mul_f32 v[28:29], v[28:29], v[92:93]
	v_pk_mul_f32 v[30:31], v[30:31], v[94:95]
	v_pk_mul_f32 v[32:33], v[32:33], v[96:97]
	v_mfma_f32_32x32x2_f32 v[34:49], v153, v223, v[34:49]
	s_waitcnt lgkmcnt(8)
	v_pk_mul_f32 v[50:51], v[50:51], v[82:83]
	v_pk_mul_f32 v[52:53], v[52:53], v[84:85]
	v_pk_mul_f32 v[54:55], v[54:55], v[86:87]
	v_pk_mul_f32 v[56:57], v[56:57], v[88:89]
	v_pk_mul_f32 v[58:59], v[58:59], v[90:91]
	v_pk_mul_f32 v[60:61], v[60:61], v[92:93]
	v_pk_mul_f32 v[62:63], v[62:63], v[94:95]
	v_pk_mul_f32 v[64:65], v[64:65], v[96:97]
	v_mfma_f32_32x32x2_f32 v[18:33], v152, v155, v[18:33]
	ds_read_b128 v[66:69], v229 offset:2304
	ds_read_b128 v[70:73], v229 offset:2336
	ds_read_b128 v[74:77], v229 offset:2368
	ds_read_b128 v[78:81], v229 offset:2400
	ds_read_b128 v[82:85], v229 offset:2432
	ds_read_b128 v[86:89], v229 offset:2464
	ds_read_b128 v[90:93], v229 offset:2496
	ds_read_b128 v[94:97], v229 offset:2528
	v_mfma_f32_32x32x2_f32 v[50:65], v154, v223, v[50:65]
	s_waitcnt lgkmcnt(14)
	v_pk_mul_f32 v[138:139], v[2:3], v[98:99]
	v_pk_mul_f32 v[140:141], v[4:5], v[100:101]
	s_waitcnt lgkmcnt(14)
	v_pk_fma_f32 v[138:139], v[6:7], v[102:103], v[138:139]
	v_pk_fma_f32 v[140:141], v[8:9], v[104:105], v[140:141]
	s_waitcnt lgkmcnt(11)
	v_pk_fma_f32 v[138:139], v[10:11], v[106:107], v[138:139]
	v_pk_fma_f32 v[140:141], v[12:13], v[108:109], v[140:141]
	s_waitcnt lgkmcnt(10)
	v_pk_fma_f32 v[138:139], v[14:15], v[110:111], v[138:139]
	v_pk_fma_f32 v[140:141], v[16:17], v[112:113], v[140:141]
	s_waitcnt lgkmcnt(14)
	v_pk_mul_f32 v[142:143], v[34:35], v[98:99]
	v_pk_mul_f32 v[144:145], v[36:37], v[100:101]
	s_waitcnt lgkmcnt(14)
	v_pk_fma_f32 v[142:143], v[38:39], v[102:103], v[142:143]
	v_pk_fma_f32 v[144:145], v[40:41], v[104:105], v[144:145]
	s_waitcnt lgkmcnt(11)
	v_pk_fma_f32 v[142:143], v[42:43], v[106:107], v[142:143]
	v_pk_fma_f32 v[144:145], v[44:45], v[108:109], v[144:145]
	s_waitcnt lgkmcnt(10)
	v_pk_fma_f32 v[142:143], v[46:47], v[110:111], v[142:143]
	v_pk_fma_f32 v[144:145], v[48:49], v[112:113], v[144:145]
	s_waitcnt lgkmcnt(13)
	v_pk_fma_f32 v[138:139], v[18:19], v[114:115], v[138:139]
	v_pk_fma_f32 v[140:141], v[20:21], v[116:117], v[140:141]
	s_waitcnt lgkmcnt(12)
	v_pk_fma_f32 v[138:139], v[22:23], v[118:119], v[138:139]
	v_pk_fma_f32 v[140:141], v[24:25], v[120:121], v[140:141]
	s_waitcnt lgkmcnt(9)
	v_pk_fma_f32 v[138:139], v[26:27], v[122:123], v[138:139]
	v_pk_fma_f32 v[140:141], v[28:29], v[124:125], v[140:141]
	s_waitcnt lgkmcnt(8)
	v_pk_fma_f32 v[138:139], v[30:31], v[126:127], v[138:139]
	v_pk_fma_f32 v[140:141], v[32:33], v[128:129], v[140:141]
	s_waitcnt lgkmcnt(13)
	v_pk_fma_f32 v[142:143], v[50:51], v[114:115], v[142:143]
	v_pk_fma_f32 v[144:145], v[52:53], v[116:117], v[144:145]
	s_waitcnt lgkmcnt(12)
	v_pk_fma_f32 v[142:143], v[54:55], v[118:119], v[142:143]
	v_pk_fma_f32 v[144:145], v[56:57], v[120:121], v[144:145]
	s_waitcnt lgkmcnt(9)
	v_pk_fma_f32 v[142:143], v[58:59], v[122:123], v[142:143]
	v_pk_fma_f32 v[144:145], v[60:61], v[124:125], v[144:145]
	s_waitcnt lgkmcnt(8)
	v_pk_fma_f32 v[142:143], v[62:63], v[126:127], v[142:143]
	v_pk_fma_f32 v[144:145], v[64:65], v[128:129], v[144:145]
	v_pk_add_f32 v[138:139], v[138:139], v[140:141]
	v_pk_add_f32 v[142:143], v[142:143], v[144:145]
	v_add_f32_e32 v226, v138, v139
	v_add_f32_e32 v227, v142, v143
	s_add_i32 s8, s8, -1
	s_addk_i32 s18, 0x90
	v_permlane32_swap_b32_e32 v226, v227
	s_addk_i32 s9, 0x600
	v_add_f32_e32 v228, v226, v227
	s_waitcnt lgkmcnt(14)
	v_bfe_u32 v234, v228, 16, 1
	v_add3_u32 v235, v228, v234, s35
	v_mad_i64_i32 v[236:237], s[20:21], v225, s31, v[146:147]
	s_cmp_eq_u32 s8, 0
	global_store_short_d16_hi v[236:237], v235, off
	s_cbranch_scc0 .LBB0_729
	s_waitcnt lgkmcnt(0)
	s_add_i32 s13, s13, 1
	s_cmp_eq_u32 s13, 26
	s_cbranch_scc0 .LBB0_701
